# MoBA list counters spread to one 128-byte line each (inside the zeroed control block): P3 appends no longer serialise on two lines per head; software-pipelined P0 weight conversion
# baseline (speedup 1.0000x reference)
.LBB0_87:
	s_cmp_gt_i32 s2, 7
	s_cselect_b64 s[24:25], -1, 0
	s_xor_b64 s[26:27], s[0:1], -1
	s_or_b64 s[24:25], s[24:25], s[26:27]
	s_mov_b64 s[42:43], -1
	s_and_b64 vcc, exec, s[24:25]
	s_cbranch_vccz .LBB0_135
	s_and_b64 s[0:1], exec, s[0:1]
	s_cselect_b32 s5, 8, 0
	s_sub_i32 s0, s2, s5
	s_lshl_b32 s15, s0, 3
	s_add_i32 s15, s15, s88
	s_cmpk_gt_i32 s15, 0x5fff
	s_mov_b32 s1, 0
	s_cbranch_scc1 .LBB0_115
	s_mul_i32 s0, s88, 0x4100
	v_lshlrev_b32_e32 v236, 2, v86
	v_add_u32_e32 v237, s0, v236
	v_and_b32_e32 v240, 7, v86
	v_lshrrev_b32_e32 v241, 3, v86
	v_mul_u32_u24_e32 v238, 0x820, v240
	v_lshl_add_u32 v238, v241, 2, v238
	v_add_u32_e32 v238, s0, v238
	v_lshlrev_b32_e32 v242, 5, v240
	v_lshlrev_b32_e32 v240, 4, v240
	s_sub_i32 s0, s3, s5
	s_lshl_b32 s56, s0, 3
	s_mov_b32 s54, s15
	s_cmpk_gt_i32 s54, 0x2fff
	s_cbranch_scc1 .Lp0t_done
	s_cmpk_lt_u32 s54, 0xa00
	s_cbranch_scc0 .Lp0t_a_m1
	s_mov_b32 s55, s54
	s_mul_i32 s0, s55, 0xcccd
	s_lshr_b32 s52, s0, 22
	s_mul_i32 s0, s52, 80
	s_sub_i32 s53, s55, s0
	s_mov_b32 s60, 0x5000
	s_mov_b32 s67, 0x1000
	s_mov_b64 s[46:47], s[34:35]
	s_add_u32 s62, s12, 0x200000
	s_addc_u32 s63, s13, 0
	s_mov_b64 s[70:71], s[20:21]
	s_mov_b32 s72, 0
	s_branch .Lp0t_a_go
.Lp0t_a_m1:
	s_cmpk_lt_u32 s54, 0xe00
	s_cbranch_scc0 .Lp0t_a_m2
	s_sub_i32 s55, s54, 0xa00
	s_lshr_b32 s52, s55, 5
	s_and_b32 s53, s55, 0x1f
	s_mov_b32 s60, 0x2000
	s_mov_b32 s67, 0x1000
	s_mov_b64 s[46:47], s[36:37]
	s_add_u32 s62, s12, 0x1600000
	s_addc_u32 s63, s13, 0
	s_mov_b64 s[70:71], s[20:21]
	s_mov_b32 s72, 0
	s_branch .Lp0t_a_go
.Lp0t_a_m2:
	s_cmpk_lt_u32 s54, 0xf00
	s_cbranch_scc0 .Lp0t_a_m3
	s_sub_i32 s55, s54, 0xe00
	s_lshr_b32 s52, s55, 3
	s_and_b32 s53, s55, 0x7
	s_mov_b32 s60, 0x800
	s_mov_b32 s67, 0x1000
	s_mov_b64 s[46:47], s[30:31]
	s_add_u32 s62, s12, 0x1e00000
	s_addc_u32 s63, s13, 0
	s_lshl_b32 s0, s52, 8
	s_add_u32 s70, s20, s0
	s_addc_u32 s71, s21, 0
	s_mov_b32 s72, 1
	s_branch .Lp0t_a_go
.Lp0t_a_m3:
	s_cmpk_lt_u32 s54, 0x1000
	s_cbranch_scc0 .Lp0t_a_m4
	s_sub_i32 s55, s54, 0xf00
	s_lshr_b32 s52, s55, 5
	s_and_b32 s53, s55, 0x1f
	s_mov_b32 s60, 0x2000
	s_mov_b32 s67, 0x400
	s_mov_b64 s[46:47], s[38:39]
	s_add_u32 s62, s12, 0x2400000
	s_addc_u32 s63, s13, 0
	s_mov_b64 s[70:71], s[20:21]
	s_mov_b32 s72, 0
	s_branch .Lp0t_a_go
.Lp0t_a_m4:
	s_cmpk_lt_u32 s54, 0x2000
	s_cbranch_scc0 .Lp0t_a_m5
	s_sub_i32 s55, s54, 0x1000
	s_lshr_b32 s52, s55, 7
	s_and_b32 s53, s55, 0x7f
	s_mov_b32 s60, 0x8000
	s_mov_b32 s67, 0x1000
	s_mov_b64 s[46:47], s[28:29]
	s_add_u32 s62, s12, 0x2600000
	s_addc_u32 s63, s13, 0
	s_lshl_b32 s0, s52, 8
	s_add_u32 s70, s22, s0
	s_addc_u32 s71, s23, 0
	s_mov_b32 s72, 1
	s_branch .Lp0t_a_go
.Lp0t_a_m5:
	s_sub_i32 s55, s54, 0x2000
	s_lshr_b32 s52, s55, 5
	s_and_b32 s53, s55, 0x1f
	s_mov_b32 s60, 0x2000
	s_mov_b32 s67, 0x4000
	s_mov_b64 s[46:47], s[40:41]
	s_add_u32 s62, s12, 0x4600000
	s_addc_u32 s63, s13, 0
	s_mov_b64 s[70:71], s[20:21]
	s_mov_b32 s72, 0
	s_branch .Lp0t_a_go
.Lp0t_a_go:
	s_lshl_b32 s0, s60, 6
	s_mul_i32 s0, s52, s0
	s_lshl_b32 s1, s53, 8
	s_add_u32 s0, s0, s1
	s_add_u32 s48, s46, s0
	s_addc_u32 s49, s47, 0
	s_lshl_b32 s0, s67, 6
	s_mul_i32 s0, s53, s0
	s_lshl_b32 s1, s52, 7
	s_add_u32 s0, s0, s1
	s_add_u32 s68, s62, s0
	s_addc_u32 s69, s63, 0
	global_load_dword v100, v236, s[48:49]
	s_add_u32 s48, s48, s60
	s_addc_u32 s49, s49, 0
	global_load_dword v101, v236, s[48:49]
	s_add_u32 s48, s48, s60
	s_addc_u32 s49, s49, 0
	global_load_dword v102, v236, s[48:49]
	s_add_u32 s48, s48, s60
	s_addc_u32 s49, s49, 0
	global_load_dword v103, v236, s[48:49]
	s_add_u32 s48, s48, s60
	s_addc_u32 s49, s49, 0
	global_load_dword v104, v236, s[48:49]
	s_add_u32 s48, s48, s60
	s_addc_u32 s49, s49, 0
	global_load_dword v105, v236, s[48:49]
	s_add_u32 s48, s48, s60
	s_addc_u32 s49, s49, 0
	global_load_dword v106, v236, s[48:49]
	s_add_u32 s48, s48, s60
	s_addc_u32 s49, s49, 0
	global_load_dword v107, v236, s[48:49]
	s_add_u32 s48, s48, s60
	s_addc_u32 s49, s49, 0
	global_load_dword v108, v236, s[48:49]
	s_add_u32 s48, s48, s60
	s_addc_u32 s49, s49, 0
	global_load_dword v109, v236, s[48:49]
	s_add_u32 s48, s48, s60
	s_addc_u32 s49, s49, 0
	global_load_dword v110, v236, s[48:49]
	s_add_u32 s48, s48, s60
	s_addc_u32 s49, s49, 0
	global_load_dword v111, v236, s[48:49]
	s_add_u32 s48, s48, s60
	s_addc_u32 s49, s49, 0
	global_load_dword v112, v236, s[48:49]
	s_add_u32 s48, s48, s60
	s_addc_u32 s49, s49, 0
	global_load_dword v113, v236, s[48:49]
	s_add_u32 s48, s48, s60
	s_addc_u32 s49, s49, 0
	global_load_dword v114, v236, s[48:49]
	s_add_u32 s48, s48, s60
	s_addc_u32 s49, s49, 0
	global_load_dword v115, v236, s[48:49]
	s_add_u32 s48, s48, s60
	s_addc_u32 s49, s49, 0
	global_load_dword v116, v236, s[48:49]
	s_add_u32 s48, s48, s60
	s_addc_u32 s49, s49, 0
	global_load_dword v117, v236, s[48:49]
	s_add_u32 s48, s48, s60
	s_addc_u32 s49, s49, 0
	global_load_dword v118, v236, s[48:49]
	s_add_u32 s48, s48, s60
	s_addc_u32 s49, s49, 0
	global_load_dword v119, v236, s[48:49]
	s_add_u32 s48, s48, s60
	s_addc_u32 s49, s49, 0
	global_load_dword v120, v236, s[48:49]
	s_add_u32 s48, s48, s60
	s_addc_u32 s49, s49, 0
	global_load_dword v121, v236, s[48:49]
	s_add_u32 s48, s48, s60
	s_addc_u32 s49, s49, 0
	global_load_dword v122, v236, s[48:49]
	s_add_u32 s48, s48, s60
	s_addc_u32 s49, s49, 0
	global_load_dword v123, v236, s[48:49]
	s_add_u32 s48, s48, s60
	s_addc_u32 s49, s49, 0
	global_load_dword v124, v236, s[48:49]
	s_add_u32 s48, s48, s60
	s_addc_u32 s49, s49, 0
	global_load_dword v125, v236, s[48:49]
	s_add_u32 s48, s48, s60
	s_addc_u32 s49, s49, 0
	global_load_dword v126, v236, s[48:49]
	s_add_u32 s48, s48, s60
	s_addc_u32 s49, s49, 0
	global_load_dword v127, v236, s[48:49]
	s_add_u32 s48, s48, s60
	s_addc_u32 s49, s49, 0
	global_load_dword v128, v236, s[48:49]
	s_add_u32 s48, s48, s60
	s_addc_u32 s49, s49, 0
	global_load_dword v129, v236, s[48:49]
	s_add_u32 s48, s48, s60
	s_addc_u32 s49, s49, 0
	global_load_dword v130, v236, s[48:49]
	s_add_u32 s48, s48, s60
	s_addc_u32 s49, s49, 0
	global_load_dword v131, v236, s[48:49]
	s_add_u32 s48, s48, s60
	s_addc_u32 s49, s49, 0
	global_load_dword v132, v236, s[48:49]
	s_add_u32 s48, s48, s60
	s_addc_u32 s49, s49, 0
	global_load_dword v133, v236, s[48:49]
	s_add_u32 s48, s48, s60
	s_addc_u32 s49, s49, 0
	global_load_dword v134, v236, s[48:49]
	s_add_u32 s48, s48, s60
	s_addc_u32 s49, s49, 0
	global_load_dword v135, v236, s[48:49]
	s_add_u32 s48, s48, s60
	s_addc_u32 s49, s49, 0
	global_load_dword v136, v236, s[48:49]
	s_add_u32 s48, s48, s60
	s_addc_u32 s49, s49, 0
	global_load_dword v137, v236, s[48:49]
	s_add_u32 s48, s48, s60
	s_addc_u32 s49, s49, 0
	global_load_dword v138, v236, s[48:49]
	s_add_u32 s48, s48, s60
	s_addc_u32 s49, s49, 0
	global_load_dword v139, v236, s[48:49]
	s_add_u32 s48, s48, s60
	s_addc_u32 s49, s49, 0
	global_load_dword v140, v236, s[48:49]
	s_add_u32 s48, s48, s60
	s_addc_u32 s49, s49, 0
	global_load_dword v141, v236, s[48:49]
	s_add_u32 s48, s48, s60
	s_addc_u32 s49, s49, 0
	global_load_dword v142, v236, s[48:49]
	s_add_u32 s48, s48, s60
	s_addc_u32 s49, s49, 0
	global_load_dword v143, v236, s[48:49]
	s_add_u32 s48, s48, s60
	s_addc_u32 s49, s49, 0
	global_load_dword v144, v236, s[48:49]
	s_add_u32 s48, s48, s60
	s_addc_u32 s49, s49, 0
	global_load_dword v145, v236, s[48:49]
	s_add_u32 s48, s48, s60
	s_addc_u32 s49, s49, 0
	global_load_dword v146, v236, s[48:49]
	s_add_u32 s48, s48, s60
	s_addc_u32 s49, s49, 0
	global_load_dword v147, v236, s[48:49]
	s_add_u32 s48, s48, s60
	s_addc_u32 s49, s49, 0
	global_load_dword v148, v236, s[48:49]
	s_add_u32 s48, s48, s60
	s_addc_u32 s49, s49, 0
	global_load_dword v149, v236, s[48:49]
	s_add_u32 s48, s48, s60
	s_addc_u32 s49, s49, 0
	global_load_dword v150, v236, s[48:49]
	s_add_u32 s48, s48, s60
	s_addc_u32 s49, s49, 0
	global_load_dword v151, v236, s[48:49]
	s_add_u32 s48, s48, s60
	s_addc_u32 s49, s49, 0
	global_load_dword v152, v236, s[48:49]
	s_add_u32 s48, s48, s60
	s_addc_u32 s49, s49, 0
	global_load_dword v153, v236, s[48:49]
	s_add_u32 s48, s48, s60
	s_addc_u32 s49, s49, 0
	global_load_dword v154, v236, s[48:49]
	s_add_u32 s48, s48, s60
	s_addc_u32 s49, s49, 0
	global_load_dword v155, v236, s[48:49]
	s_add_u32 s48, s48, s60
	s_addc_u32 s49, s49, 0
	global_load_dword v156, v236, s[48:49]
	s_add_u32 s48, s48, s60
	s_addc_u32 s49, s49, 0
	global_load_dword v157, v236, s[48:49]
	s_add_u32 s48, s48, s60
	s_addc_u32 s49, s49, 0
	global_load_dword v158, v236, s[48:49]
	s_add_u32 s48, s48, s60
	s_addc_u32 s49, s49, 0
	global_load_dword v159, v236, s[48:49]
	s_add_u32 s48, s48, s60
	s_addc_u32 s49, s49, 0
	global_load_dword v160, v236, s[48:49]
	s_add_u32 s48, s48, s60
	s_addc_u32 s49, s49, 0
	global_load_dword v161, v236, s[48:49]
	s_add_u32 s48, s48, s60
	s_addc_u32 s49, s49, 0
	global_load_dword v162, v236, s[48:49]
	s_add_u32 s48, s48, s60
	s_addc_u32 s49, s49, 0
	global_load_dword v163, v236, s[48:49]
	global_load_dword v243, v236, s[48:49]
	global_load_dword v243, v236, s[48:49]
	global_load_dword v243, v236, s[48:49]
	global_load_dword v243, v236, s[48:49]
	global_load_dword v243, v236, s[48:49]
	global_load_dword v243, v236, s[48:49]
	global_load_dword v243, v236, s[48:49]
	global_load_dword v243, v236, s[48:49]
	s_mov_b32 s61, s67
	s_mov_b64 s[50:51], s[68:69]
	s_mov_b64 s[64:65], s[70:71]
	s_mov_b32 s66, s72
.Lp0t_loop:
	global_load_dwordx4 v[228:231], v242, s[64:65]
	global_load_dwordx4 v[232:235], v242, s[64:65] offset:16
	s_waitcnt vmcnt(63)
	ds_write_b32 v237, v100 offset:0
	ds_write_b32 v237, v101 offset:260
	ds_write_b32 v237, v102 offset:520
	ds_write_b32 v237, v103 offset:780
	ds_write_b32 v237, v104 offset:1040
	ds_write_b32 v237, v105 offset:1300
	ds_write_b32 v237, v106 offset:1560
	ds_write_b32 v237, v107 offset:1820
	s_waitcnt vmcnt(58)
	ds_write_b32 v237, v108 offset:2080
	ds_write_b32 v237, v109 offset:2340
	ds_write_b32 v237, v110 offset:2600
	ds_write_b32 v237, v111 offset:2860
	ds_write_b32 v237, v112 offset:3120
	ds_write_b32 v237, v113 offset:3380
	ds_write_b32 v237, v114 offset:3640
	ds_write_b32 v237, v115 offset:3900
	s_waitcnt vmcnt(50)
	ds_write_b32 v237, v116 offset:4160
	ds_write_b32 v237, v117 offset:4420
	ds_write_b32 v237, v118 offset:4680
	ds_write_b32 v237, v119 offset:4940
	ds_write_b32 v237, v120 offset:5200
	ds_write_b32 v237, v121 offset:5460
	ds_write_b32 v237, v122 offset:5720
	ds_write_b32 v237, v123 offset:5980
	s_waitcnt vmcnt(42)
	ds_write_b32 v237, v124 offset:6240
	ds_write_b32 v237, v125 offset:6500
	ds_write_b32 v237, v126 offset:6760
	ds_write_b32 v237, v127 offset:7020
	ds_write_b32 v237, v128 offset:7280
	ds_write_b32 v237, v129 offset:7540
	ds_write_b32 v237, v130 offset:7800
	ds_write_b32 v237, v131 offset:8060
	s_waitcnt vmcnt(34)
	ds_write_b32 v237, v132 offset:8320
	ds_write_b32 v237, v133 offset:8580
	ds_write_b32 v237, v134 offset:8840
	ds_write_b32 v237, v135 offset:9100
	ds_write_b32 v237, v136 offset:9360
	ds_write_b32 v237, v137 offset:9620
	ds_write_b32 v237, v138 offset:9880
	ds_write_b32 v237, v139 offset:10140
	s_waitcnt vmcnt(26)
	ds_write_b32 v237, v140 offset:10400
	ds_write_b32 v237, v141 offset:10660
	ds_write_b32 v237, v142 offset:10920
	ds_write_b32 v237, v143 offset:11180
	ds_write_b32 v237, v144 offset:11440
	ds_write_b32 v237, v145 offset:11700
	ds_write_b32 v237, v146 offset:11960
	ds_write_b32 v237, v147 offset:12220
	s_waitcnt vmcnt(18)
	ds_write_b32 v237, v148 offset:12480
	ds_write_b32 v237, v149 offset:12740
	ds_write_b32 v237, v150 offset:13000
	ds_write_b32 v237, v151 offset:13260
	ds_write_b32 v237, v152 offset:13520
	ds_write_b32 v237, v153 offset:13780
	ds_write_b32 v237, v154 offset:14040
	ds_write_b32 v237, v155 offset:14300
	s_waitcnt vmcnt(10)
	ds_write_b32 v237, v156 offset:14560
	ds_write_b32 v237, v157 offset:14820
	ds_write_b32 v237, v158 offset:15080
	ds_write_b32 v237, v159 offset:15340
	ds_write_b32 v237, v160 offset:15600
	ds_write_b32 v237, v161 offset:15860
	ds_write_b32 v237, v162 offset:16120
	ds_write_b32 v237, v163 offset:16380
	s_waitcnt vmcnt(0) lgkmcnt(0)
	s_add_i32 s54, s54, s56
	s_mov_b32 s73, 0
	s_cmpk_gt_i32 s54, 0x2fff
	s_cbranch_scc1 .Lp0t_nonext
	s_mov_b32 s73, 1
	s_cmpk_lt_u32 s54, 0xa00
	s_cbranch_scc0 .Lp0t_b_m1
	s_mov_b32 s55, s54
	s_mul_i32 s0, s55, 0xcccd
	s_lshr_b32 s52, s0, 22
	s_mul_i32 s0, s52, 80
	s_sub_i32 s53, s55, s0
	s_mov_b32 s60, 0x5000
	s_mov_b32 s67, 0x1000
	s_mov_b64 s[46:47], s[34:35]
	s_add_u32 s62, s12, 0x200000
	s_addc_u32 s63, s13, 0
	s_mov_b64 s[70:71], s[20:21]
	s_mov_b32 s72, 0
	s_branch .Lp0t_b_go

.Lp0t_b_go:
	s_lshl_b32 s0, s60, 6
	s_mul_i32 s0, s52, s0
	s_lshl_b32 s1, s53, 8
	s_add_u32 s0, s0, s1
	s_add_u32 s48, s46, s0
	s_addc_u32 s49, s47, 0
	s_lshl_b32 s0, s67, 6
	s_mul_i32 s0, s53, s0
	s_lshl_b32 s1, s52, 7
	s_add_u32 s0, s0, s1
	s_add_u32 s68, s62, s0
	s_addc_u32 s69, s63, 0
	global_load_dword v100, v236, s[48:49]
	s_add_u32 s48, s48, s60
	s_addc_u32 s49, s49, 0
	global_load_dword v101, v236, s[48:49]
	s_add_u32 s48, s48, s60
	s_addc_u32 s49, s49, 0
	global_load_dword v102, v236, s[48:49]
	s_add_u32 s48, s48, s60
	s_addc_u32 s49, s49, 0
	global_load_dword v103, v236, s[48:49]
	s_add_u32 s48, s48, s60
	s_addc_u32 s49, s49, 0
	global_load_dword v104, v236, s[48:49]
	s_add_u32 s48, s48, s60
	s_addc_u32 s49, s49, 0
	global_load_dword v105, v236, s[48:49]
	s_add_u32 s48, s48, s60
	s_addc_u32 s49, s49, 0
	global_load_dword v106, v236, s[48:49]
	s_add_u32 s48, s48, s60
	s_addc_u32 s49, s49, 0
	global_load_dword v107, v236, s[48:49]
	s_add_u32 s48, s48, s60
	s_addc_u32 s49, s49, 0
	global_load_dword v108, v236, s[48:49]
	s_add_u32 s48, s48, s60
	s_addc_u32 s49, s49, 0
	global_load_dword v109, v236, s[48:49]
	s_add_u32 s48, s48, s60
	s_addc_u32 s49, s49, 0
	global_load_dword v110, v236, s[48:49]
	s_add_u32 s48, s48, s60
	s_addc_u32 s49, s49, 0
	global_load_dword v111, v236, s[48:49]
	s_add_u32 s48, s48, s60
	s_addc_u32 s49, s49, 0
	global_load_dword v112, v236, s[48:49]
	s_add_u32 s48, s48, s60
	s_addc_u32 s49, s49, 0
	global_load_dword v113, v236, s[48:49]
	s_add_u32 s48, s48, s60
	s_addc_u32 s49, s49, 0
	global_load_dword v114, v236, s[48:49]
	s_add_u32 s48, s48, s60
	s_addc_u32 s49, s49, 0
	global_load_dword v115, v236, s[48:49]
	s_add_u32 s48, s48, s60
	s_addc_u32 s49, s49, 0
	global_load_dword v116, v236, s[48:49]
	s_add_u32 s48, s48, s60
	s_addc_u32 s49, s49, 0
	global_load_dword v117, v236, s[48:49]
	s_add_u32 s48, s48, s60
	s_addc_u32 s49, s49, 0
	global_load_dword v118, v236, s[48:49]
	s_add_u32 s48, s48, s60
	s_addc_u32 s49, s49, 0
	global_load_dword v119, v236, s[48:49]
	s_add_u32 s48, s48, s60
	s_addc_u32 s49, s49, 0
	global_load_dword v120, v236, s[48:49]
	s_add_u32 s48, s48, s60
	s_addc_u32 s49, s49, 0
	global_load_dword v121, v236, s[48:49]
	s_add_u32 s48, s48, s60
	s_addc_u32 s49, s49, 0
	global_load_dword v122, v236, s[48:49]
	s_add_u32 s48, s48, s60
	s_addc_u32 s49, s49, 0
	global_load_dword v123, v236, s[48:49]
	s_add_u32 s48, s48, s60
	s_addc_u32 s49, s49, 0
	global_load_dword v124, v236, s[48:49]
	s_add_u32 s48, s48, s60
	s_addc_u32 s49, s49, 0
	global_load_dword v125, v236, s[48:49]
	s_add_u32 s48, s48, s60
	s_addc_u32 s49, s49, 0
	global_load_dword v126, v236, s[48:49]
	s_add_u32 s48, s48, s60
	s_addc_u32 s49, s49, 0
	global_load_dword v127, v236, s[48:49]
	s_add_u32 s48, s48, s60
	s_addc_u32 s49, s49, 0
	global_load_dword v128, v236, s[48:49]
	s_add_u32 s48, s48, s60
	s_addc_u32 s49, s49, 0
	global_load_dword v129, v236, s[48:49]
	s_add_u32 s48, s48, s60
	s_addc_u32 s49, s49, 0
	global_load_dword v130, v236, s[48:49]
	s_add_u32 s48, s48, s60
	s_addc_u32 s49, s49, 0
	global_load_dword v131, v236, s[48:49]
	s_add_u32 s48, s48, s60
	s_addc_u32 s49, s49, 0
	global_load_dword v132, v236, s[48:49]
	s_add_u32 s48, s48, s60
	s_addc_u32 s49, s49, 0
	global_load_dword v133, v236, s[48:49]
	s_add_u32 s48, s48, s60
	s_addc_u32 s49, s49, 0
	global_load_dword v134, v236, s[48:49]
	s_add_u32 s48, s48, s60
	s_addc_u32 s49, s49, 0
	global_load_dword v135, v236, s[48:49]
	s_add_u32 s48, s48, s60
	s_addc_u32 s49, s49, 0
	global_load_dword v136, v236, s[48:49]
	s_add_u32 s48, s48, s60
	s_addc_u32 s49, s49, 0
	global_load_dword v137, v236, s[48:49]
	s_add_u32 s48, s48, s60
	s_addc_u32 s49, s49, 0
	global_load_dword v138, v236, s[48:49]
	s_add_u32 s48, s48, s60
	s_addc_u32 s49, s49, 0
	global_load_dword v139, v236, s[48:49]
	s_add_u32 s48, s48, s60
	s_addc_u32 s49, s49, 0
	global_load_dword v140, v236, s[48:49]
	s_add_u32 s48, s48, s60
	s_addc_u32 s49, s49, 0
	global_load_dword v141, v236, s[48:49]
	s_add_u32 s48, s48, s60
	s_addc_u32 s49, s49, 0
	global_load_dword v142, v236, s[48:49]
	s_add_u32 s48, s48, s60
	s_addc_u32 s49, s49, 0
	global_load_dword v143, v236, s[48:49]
	s_add_u32 s48, s48, s60
	s_addc_u32 s49, s49, 0
	global_load_dword v144, v236, s[48:49]
	s_add_u32 s48, s48, s60
	s_addc_u32 s49, s49, 0
	global_load_dword v145, v236, s[48:49]
	s_add_u32 s48, s48, s60
	s_addc_u32 s49, s49, 0
	global_load_dword v146, v236, s[48:49]
	s_add_u32 s48, s48, s60
	s_addc_u32 s49, s49, 0
	global_load_dword v147, v236, s[48:49]
	s_add_u32 s48, s48, s60
	s_addc_u32 s49, s49, 0
	global_load_dword v148, v236, s[48:49]
	s_add_u32 s48, s48, s60
	s_addc_u32 s49, s49, 0
	global_load_dword v149, v236, s[48:49]
	s_add_u32 s48, s48, s60
	s_addc_u32 s49, s49, 0
	global_load_dword v150, v236, s[48:49]
	s_add_u32 s48, s48, s60
	s_addc_u32 s49, s49, 0
	global_load_dword v151, v236, s[48:49]
	s_add_u32 s48, s48, s60
	s_addc_u32 s49, s49, 0
	global_load_dword v152, v236, s[48:49]
	s_add_u32 s48, s48, s60
	s_addc_u32 s49, s49, 0
	global_load_dword v153, v236, s[48:49]
	s_add_u32 s48, s48, s60
	s_addc_u32 s49, s49, 0
	global_load_dword v154, v236, s[48:49]
	s_add_u32 s48, s48, s60
	s_addc_u32 s49, s49, 0
	global_load_dword v155, v236, s[48:49]
	s_add_u32 s48, s48, s60
	s_addc_u32 s49, s49, 0
	global_load_dword v156, v236, s[48:49]
	s_add_u32 s48, s48, s60
	s_addc_u32 s49, s49, 0
	global_load_dword v157, v236, s[48:49]
	s_add_u32 s48, s48, s60
	s_addc_u32 s49, s49, 0
	global_load_dword v158, v236, s[48:49]
	s_add_u32 s48, s48, s60
	s_addc_u32 s49, s49, 0
	global_load_dword v159, v236, s[48:49]
	s_add_u32 s48, s48, s60
	s_addc_u32 s49, s49, 0
	global_load_dword v160, v236, s[48:49]
	s_add_u32 s48, s48, s60
	s_addc_u32 s49, s49, 0
	global_load_dword v161, v236, s[48:49]
	s_add_u32 s48, s48, s60
	s_addc_u32 s49, s49, 0
	global_load_dword v162, v236, s[48:49]
	s_add_u32 s48, s48, s60
	s_addc_u32 s49, s49, 0
	global_load_dword v163, v236, s[48:49]
.Lp0t_nonext:
	ds_read_b32 v164, v238 offset:0
	ds_read_b32 v165, v238 offset:260
	ds_read_b32 v166, v238 offset:520
	ds_read_b32 v167, v238 offset:780
	ds_read_b32 v168, v238 offset:1040
	ds_read_b32 v169, v238 offset:1300
	ds_read_b32 v170, v238 offset:1560
	ds_read_b32 v171, v238 offset:1820
	ds_read_b32 v172, v238 offset:32
	ds_read_b32 v173, v238 offset:292
	ds_read_b32 v174, v238 offset:552
	ds_read_b32 v175, v238 offset:812
	ds_read_b32 v176, v238 offset:1072
	ds_read_b32 v177, v238 offset:1332
	ds_read_b32 v178, v238 offset:1592
	ds_read_b32 v179, v238 offset:1852
	ds_read_b32 v180, v238 offset:64
	ds_read_b32 v181, v238 offset:324
	ds_read_b32 v182, v238 offset:584
	ds_read_b32 v183, v238 offset:844
	ds_read_b32 v184, v238 offset:1104
	ds_read_b32 v185, v238 offset:1364
	ds_read_b32 v186, v238 offset:1624
	ds_read_b32 v187, v238 offset:1884
	ds_read_b32 v188, v238 offset:96
	ds_read_b32 v189, v238 offset:356
	ds_read_b32 v190, v238 offset:616
	ds_read_b32 v191, v238 offset:876
	ds_read_b32 v192, v238 offset:1136
	ds_read_b32 v193, v238 offset:1396
	ds_read_b32 v194, v238 offset:1656
	ds_read_b32 v195, v238 offset:1916
	ds_read_b32 v196, v238 offset:128
	ds_read_b32 v197, v238 offset:388
	ds_read_b32 v198, v238 offset:648
	ds_read_b32 v199, v238 offset:908
	ds_read_b32 v200, v238 offset:1168
	ds_read_b32 v201, v238 offset:1428
	ds_read_b32 v202, v238 offset:1688
	ds_read_b32 v203, v238 offset:1948
	ds_read_b32 v204, v238 offset:160
	ds_read_b32 v205, v238 offset:420
	ds_read_b32 v206, v238 offset:680
	ds_read_b32 v207, v238 offset:940
	ds_read_b32 v208, v238 offset:1200
	ds_read_b32 v209, v238 offset:1460
	ds_read_b32 v210, v238 offset:1720
	ds_read_b32 v211, v238 offset:1980
	ds_read_b32 v212, v238 offset:192
	ds_read_b32 v213, v238 offset:452
	ds_read_b32 v214, v238 offset:712
	ds_read_b32 v215, v238 offset:972
	ds_read_b32 v216, v238 offset:1232
	ds_read_b32 v217, v238 offset:1492
	ds_read_b32 v218, v238 offset:1752
	ds_read_b32 v219, v238 offset:2012
	ds_read_b32 v220, v238 offset:224
	ds_read_b32 v221, v238 offset:484
	ds_read_b32 v222, v238 offset:744
	ds_read_b32 v223, v238 offset:1004
	ds_read_b32 v224, v238 offset:1264
	ds_read_b32 v225, v238 offset:1524
	ds_read_b32 v226, v238 offset:1784
	ds_read_b32 v227, v238 offset:2044
	v_mul_lo_u32 v239, v241, s61
	v_add_u32_e32 v239, v239, v240
	s_waitcnt lgkmcnt(0)
	s_cmp_eq_u32 s66, 0
	s_cbranch_scc1 .Lp0t_nogk2
	v_mul_f32_e32 v164, v164, v228
	v_mul_f32_e32 v165, v165, v229
	v_mul_f32_e32 v166, v166, v230
	v_mul_f32_e32 v167, v167, v231
	v_mul_f32_e32 v168, v168, v232
	v_mul_f32_e32 v169, v169, v233
	v_mul_f32_e32 v170, v170, v234
	v_mul_f32_e32 v171, v171, v235
	v_mul_f32_e32 v172, v172, v228
	v_mul_f32_e32 v173, v173, v229
	v_mul_f32_e32 v174, v174, v230
	v_mul_f32_e32 v175, v175, v231
	v_mul_f32_e32 v176, v176, v232
	v_mul_f32_e32 v177, v177, v233
	v_mul_f32_e32 v178, v178, v234
	v_mul_f32_e32 v179, v179, v235
	v_mul_f32_e32 v180, v180, v228
	v_mul_f32_e32 v181, v181, v229
	v_mul_f32_e32 v182, v182, v230
	v_mul_f32_e32 v183, v183, v231
	v_mul_f32_e32 v184, v184, v232
	v_mul_f32_e32 v185, v185, v233
	v_mul_f32_e32 v186, v186, v234
	v_mul_f32_e32 v187, v187, v235
	v_mul_f32_e32 v188, v188, v228
	v_mul_f32_e32 v189, v189, v229
	v_mul_f32_e32 v190, v190, v230
	v_mul_f32_e32 v191, v191, v231
	v_mul_f32_e32 v192, v192, v232
	v_mul_f32_e32 v193, v193, v233
	v_mul_f32_e32 v194, v194, v234
	v_mul_f32_e32 v195, v195, v235
	v_mul_f32_e32 v196, v196, v228
	v_mul_f32_e32 v197, v197, v229
	v_mul_f32_e32 v198, v198, v230
	v_mul_f32_e32 v199, v199, v231
	v_mul_f32_e32 v200, v200, v232
	v_mul_f32_e32 v201, v201, v233
	v_mul_f32_e32 v202, v202, v234
	v_mul_f32_e32 v203, v203, v235
	v_mul_f32_e32 v204, v204, v228
	v_mul_f32_e32 v205, v205, v229
	v_mul_f32_e32 v206, v206, v230
	v_mul_f32_e32 v207, v207, v231
	v_mul_f32_e32 v208, v208, v232
	v_mul_f32_e32 v209, v209, v233
	v_mul_f32_e32 v210, v210, v234
	v_mul_f32_e32 v211, v211, v235
	v_mul_f32_e32 v212, v212, v228
	v_mul_f32_e32 v213, v213, v229
	v_mul_f32_e32 v214, v214, v230
	v_mul_f32_e32 v215, v215, v231
	v_mul_f32_e32 v216, v216, v232
	v_mul_f32_e32 v217, v217, v233
	v_mul_f32_e32 v218, v218, v234
	v_mul_f32_e32 v219, v219, v235
	v_mul_f32_e32 v220, v220, v228
	v_mul_f32_e32 v221, v221, v229
	v_mul_f32_e32 v222, v222, v230
	v_mul_f32_e32 v223, v223, v231
	v_mul_f32_e32 v224, v224, v232
	v_mul_f32_e32 v225, v225, v233
	v_mul_f32_e32 v226, v226, v234
	v_mul_f32_e32 v227, v227, v235
.Lp0t_nogk2:
	v_cvt_pk_bf16_f32 v164, v164, v165
	v_cvt_pk_bf16_f32 v165, v166, v167
	v_cvt_pk_bf16_f32 v166, v168, v169
	v_cvt_pk_bf16_f32 v167, v170, v171
	v_cvt_pk_bf16_f32 v172, v172, v173
	v_cvt_pk_bf16_f32 v173, v174, v175
	v_cvt_pk_bf16_f32 v174, v176, v177
	v_cvt_pk_bf16_f32 v175, v178, v179
	v_cvt_pk_bf16_f32 v180, v180, v181
	v_cvt_pk_bf16_f32 v181, v182, v183
	v_cvt_pk_bf16_f32 v182, v184, v185
	v_cvt_pk_bf16_f32 v183, v186, v187
	v_cvt_pk_bf16_f32 v188, v188, v189
	v_cvt_pk_bf16_f32 v189, v190, v191
	v_cvt_pk_bf16_f32 v190, v192, v193
	v_cvt_pk_bf16_f32 v191, v194, v195
	v_cvt_pk_bf16_f32 v196, v196, v197
	v_cvt_pk_bf16_f32 v197, v198, v199
	v_cvt_pk_bf16_f32 v198, v200, v201
	v_cvt_pk_bf16_f32 v199, v202, v203
	v_cvt_pk_bf16_f32 v204, v204, v205
	v_cvt_pk_bf16_f32 v205, v206, v207
	v_cvt_pk_bf16_f32 v206, v208, v209
	v_cvt_pk_bf16_f32 v207, v210, v211
	v_cvt_pk_bf16_f32 v212, v212, v213
	v_cvt_pk_bf16_f32 v213, v214, v215
	v_cvt_pk_bf16_f32 v214, v216, v217
	v_cvt_pk_bf16_f32 v215, v218, v219
	v_cvt_pk_bf16_f32 v220, v220, v221
	v_cvt_pk_bf16_f32 v221, v222, v223
	v_cvt_pk_bf16_f32 v222, v224, v225
	v_cvt_pk_bf16_f32 v223, v226, v227
	s_lshl_b32 s0, s61, 3
	global_store_dwordx4 v239, v[164:167], s[50:51]
	s_add_u32 s50, s50, s0
	s_addc_u32 s51, s51, 0
	global_store_dwordx4 v239, v[172:175], s[50:51]
	s_add_u32 s50, s50, s0
	s_addc_u32 s51, s51, 0
	global_store_dwordx4 v239, v[180:183], s[50:51]
	s_add_u32 s50, s50, s0
	s_addc_u32 s51, s51, 0
	global_store_dwordx4 v239, v[188:191], s[50:51]
	s_add_u32 s50, s50, s0
	s_addc_u32 s51, s51, 0
	global_store_dwordx4 v239, v[196:199], s[50:51]
	s_add_u32 s50, s50, s0
	s_addc_u32 s51, s51, 0
	global_store_dwordx4 v239, v[204:207], s[50:51]
	s_add_u32 s50, s50, s0
	s_addc_u32 s51, s51, 0
	global_store_dwordx4 v239, v[212:215], s[50:51]
	s_add_u32 s50, s50, s0
	s_addc_u32 s51, s51, 0
	global_store_dwordx4 v239, v[220:223], s[50:51]
	s_cmp_eq_u32 s73, 0
	s_cbranch_scc1 .Lp0t_done
	s_mov_b32 s61, s67
	s_mov_b64 s[50:51], s[68:69]
	s_mov_b64 s[64:65], s[70:71]
	s_mov_b32 s66, s72
	s_branch .Lp0t_loop

.LBB0_651:
	s_and_b32 s6, s54, 0xff
	s_waitcnt lgkmcnt(0)
	v_cmp_eq_u16_sdwa s[40:41], v20, s6 src0_sel:BYTE_0 src1_sel:DWORD
	v_cmp_eq_u16_sdwa s[38:39], v13, s6 src0_sel:BYTE_0 src1_sel:DWORD
	s_bcnt1_i32_b64 s65, s[40:41]
	s_bcnt1_i32_b64 s64, s[38:39]
	v_cmp_eq_u16_sdwa s[36:37], v14, s6 src0_sel:BYTE_0 src1_sel:DWORD
	s_add_i32 s7, s65, s64
	s_bcnt1_i32_b64 s63, s[36:37]
	v_cmp_eq_u16_sdwa s[34:35], v15, s6 src0_sel:BYTE_0 src1_sel:DWORD
	s_add_i32 s7, s7, s63
	s_bcnt1_i32_b64 s62, s[34:35]
	v_cmp_eq_u16_sdwa s[30:31], v16, s6 src0_sel:BYTE_0 src1_sel:DWORD
	s_add_i32 s7, s7, s62
	s_bcnt1_i32_b64 s61, s[30:31]
	v_cmp_eq_u16_sdwa s[28:29], v17, s6 src0_sel:BYTE_0 src1_sel:DWORD
	s_add_i32 s7, s7, s61
	s_bcnt1_i32_b64 s60, s[28:29]
	v_cmp_eq_u16_sdwa s[22:23], v18, s6 src0_sel:BYTE_0 src1_sel:DWORD
	s_add_i32 s7, s7, s60
	s_bcnt1_i32_b64 s59, s[22:23]
	v_cmp_eq_u16_sdwa s[20:21], v19, s6 src0_sel:BYTE_0 src1_sel:DWORD
	s_add_i32 s7, s7, s59
	s_bcnt1_i32_b64 s58, s[20:21]
	v_cmp_eq_u16_sdwa s[18:19], v1, s6 src0_sel:BYTE_0 src1_sel:DWORD
	s_add_i32 s7, s7, s58
	s_bcnt1_i32_b64 s57, s[18:19]
	v_cmp_eq_u16_sdwa s[16:17], v2, s6 src0_sel:BYTE_0 src1_sel:DWORD
	s_add_i32 s7, s7, s57
	s_bcnt1_i32_b64 s56, s[16:17]
	v_cmp_eq_u16_sdwa s[14:15], v3, s6 src0_sel:BYTE_0 src1_sel:DWORD
	s_add_i32 s7, s7, s56
	s_bcnt1_i32_b64 s55, s[14:15]
	s_add_i32 s10, s7, s55
	v_cmp_eq_u16_sdwa s[6:7], v4, s6 src0_sel:BYTE_0 src1_sel:DWORD
	s_bcnt1_i32_b64 s42, s[6:7]
	s_add_i32 s10, s10, s42
	s_cmp_eq_u32 s10, 0
	s_cbranch_scc1 .LBB0_650
	s_add_i32 s42, s53, s54
	s_ashr_i32 s43, s42, 31
	v_mov_b32_e32 v24, 0
	s_and_saveexec_b64 s[44:45], s[4:5]
	s_cbranch_execz .LBB0_656
	s_mov_b64 s[48:49], exec
	v_mbcnt_lo_u32_b32 v24, s48, 0
	v_mbcnt_hi_u32_b32 v24, s49, v24
	v_cmp_eq_u32_e32 vcc, 0, v24
	s_and_saveexec_b64 s[46:47], vcc
	s_cbranch_execz .LBB0_655
	s_lshl_b64 s[66:67], s[42:43], 7
	s_add_u32 s66, s25, s66
	s_addc_u32 s67, s24, s67
	s_add_u32 s66, s66, 0x10000
	s_addc_u32 s67, s67, 0
	s_bcnt1_i32_b64 s48, s[48:49]
	s_mul_i32 s48, s10, s48
	v_mov_b32_e32 v25, s48
	global_atomic_add v25, v65, v25, s[66:67] sc0

.LBB0_771:
	s_cmp_lt_i32 s74, 5
	s_cselect_b64 s[4:5], -1, 0
	s_and_b64 s[6:7], s[4:5], s[0:1]
	s_andn2_b64 vcc, exec, s[6:7]
	s_cbranch_vccnz .LBB0_882
	v_mbcnt_lo_u32_b32 v0, -1, 0
	s_add_i32 s0, 0, 0x250a8
	v_mbcnt_hi_u32_b32 v3, -1, v0
	v_mov_b32_e32 v0, s0
	ds_read_b64 v[4:5], v0
	s_and_b32 s0, s78, 0xffffffc0
	v_add_u32_e32 v2, s0, v3
	v_lshlrev_b32_e32 v0, 1, v2
	v_ashrrev_i32_e32 v1, 31, v0
	s_waitcnt lgkmcnt(0)
	v_readfirstlane_b32 s29, v5
	v_readfirstlane_b32 s28, v4
	v_add_u32_e32 v7, -2, v3
	v_add_u32_e32 v8, -4, v3
	s_add_u32 s98, s28, 0x10000
	s_addc_u32 s99, s29, 0
	v_lshlrev_b32_e32 v4, 7, v0
	global_load_dword v1, v4, s[98:99] sc1
	global_load_dword v6, v4, s[98:99] offset:128 sc1
	v_and_b32_e32 v4, 64, v3
	v_add_u32_e32 v5, -1, v3
	v_cmp_lt_i32_e32 vcc, v5, v4
	v_add_u32_e32 v9, -8, v3
	v_add_u32_e32 v10, -16, v3
	v_cndmask_b32_e32 v5, v5, v3, vcc
	v_lshlrev_b32_e32 v5, 2, v5
	v_cmp_lt_i32_e32 vcc, v7, v4
	v_cmp_lt_i32_e64 s[4:5], 31, v3
	s_waitcnt vmcnt(0)
	v_add_u32_e32 v1, 31, v1
	v_add_u32_e32 v6, 31, v6
	v_lshrrev_b32_e32 v11, 5, v1
	v_lshrrev_b32_e32 v1, 5, v6
	v_min_u32_e32 v12, 1, v11
	v_add_u32_e32 v13, 7, v11
	v_and_b32_e32 v13, -8, v13
	v_mad_u32_u24 v11, v12, 8, v13
	v_min_u32_e32 v12, 1, v1
	v_add_u32_e32 v13, 7, v1
	v_and_b32_e32 v13, -8, v13
	v_mad_u32_u24 v1, v12, 8, v13
	v_add_u32_e32 v6, v1, v11
	ds_bpermute_b32 v5, v5, v6
	v_cndmask_b32_e32 v7, v7, v3, vcc
	v_cmp_lt_i32_e32 vcc, 0, v3
	v_lshlrev_b32_e32 v7, 2, v7
	s_waitcnt lgkmcnt(0)
	v_cndmask_b32_e32 v5, 0, v5, vcc
	v_add_u32_e32 v5, v5, v6
	ds_bpermute_b32 v6, v7, v5
	v_cmp_lt_i32_e32 vcc, v8, v4
	s_nop 1
	v_cndmask_b32_e32 v7, v8, v3, vcc
	v_cmp_lt_i32_e32 vcc, 1, v3
	v_lshlrev_b32_e32 v7, 2, v7
	s_waitcnt lgkmcnt(0)
	v_cndmask_b32_e32 v6, 0, v6, vcc
	v_add_u32_e32 v5, v6, v5
	ds_bpermute_b32 v6, v7, v5
	v_cmp_lt_i32_e32 vcc, v9, v4
	s_nop 1
	v_cndmask_b32_e32 v7, v9, v3, vcc
	v_cmp_lt_i32_e32 vcc, 3, v3
	v_lshlrev_b32_e32 v7, 2, v7
	s_waitcnt lgkmcnt(0)
	v_cndmask_b32_e32 v6, 0, v6, vcc
	v_add_u32_e32 v5, v6, v5
	ds_bpermute_b32 v6, v7, v5
	v_cmp_lt_i32_e32 vcc, v10, v4
	s_nop 1
	v_cndmask_b32_e32 v7, v10, v3, vcc
	v_cmp_lt_i32_e32 vcc, 7, v3
	v_lshlrev_b32_e32 v7, 2, v7
	s_waitcnt lgkmcnt(0)
	v_cndmask_b32_e32 v6, 0, v6, vcc
	v_add_u32_e32 v5, v6, v5
	ds_bpermute_b32 v6, v7, v5
	v_subrev_co_u32_e64 v7, s[0:1], 32, v3
	v_cmp_lt_i32_e32 vcc, v7, v4
	s_nop 1
	v_cndmask_b32_e32 v4, v7, v3, vcc
	v_cmp_lt_i32_e32 vcc, 15, v3
	v_lshlrev_b32_e32 v4, 2, v4
	s_waitcnt lgkmcnt(0)
	v_cndmask_b32_e32 v6, 0, v6, vcc
	v_add_u32_e32 v5, v6, v5
	ds_bpermute_b32 v4, v4, v5
	v_cmp_eq_u32_e32 vcc, 63, v3
	s_waitcnt lgkmcnt(0)
	v_cndmask_b32_e64 v4, 0, v4, s[4:5]
	v_add_u32_e32 v8, v4, v5
	s_and_saveexec_b64 s[4:5], vcc
	s_lshl_b32 s8, s73, 2
	s_add_i32 s8, s8, 0
	s_add_i32 s8, s8, 0x23800
	v_mov_b32_e32 v4, s8
	ds_write_b32 v4, v8
	s_or_b64 exec, exec, s[4:5]
	s_cmp_lt_u32 s78, 64
	v_mov_b32_e32 v4, 0
	s_waitcnt lgkmcnt(0)
	s_barrier
	s_cbranch_scc1 .LBB0_787
	s_cmpk_lt_u32 s78, 0x100
	s_cbranch_scc1 .LBB0_780
	s_add_i32 s9, s73, -4
	s_lshr_b32 s8, s9, 2
	s_add_i32 s8, s8, 1
	s_mov_b32 s4, 0
	s_cmp_lt_u32 s9, 28
	s_cbranch_scc1 .LBB0_781
	s_add_i32 s5, 0, 0x23800
	s_and_b32 s9, s8, 0x7ffffff8
	v_mov_b32_e32 v7, 0
	v_mov_b32_e32 v6, 0
	v_mov_b32_e32 v5, 0
	v_mov_b32_e32 v4, 0

.LBB0_800:
	s_lshl_b32 s8, s34, 2
	s_ashr_i32 s35, s34, 31
	s_add_i32 s59, s8, 0
	s_add_i32 s8, s59, 0x24000
	s_lshl_b64 s[10:11], s[34:35], 7
	s_add_u32 s10, s28, s10
	v_mov_b32_e32 v2, s8
	s_addc_u32 s11, s29, s11
	s_add_u32 s10, s10, 0x10000
	s_addc_u32 s11, s11, 0
	ds_read_b32 v100, v2
	global_load_dword v101, v1, s[10:11] sc1
	s_lshl_b32 s10, s34, 5
	s_and_b32 s60, s10, 0xffffc000
	s_lshl_b32 s10, s34, 8
	s_and_b32 s61, s10, 0x3f00
	s_or_b32 s10, s60, s61
	s_ashr_i32 s8, s34, 6
	s_ashr_i32 s11, s10, 31
	s_and_b32 s58, s8, 7
	s_lshl_b64 s[10:11], s[10:11], 11
	s_add_u32 s10, s27, s10
	s_addc_u32 s11, s31, s11
	s_lshl_b32 s12, s58, 8
	s_add_u32 s10, s10, s12
	s_addc_u32 s11, s11, 0
	v_lshl_add_u64 v[14:15], s[10:11], 0, v[176:177]
	v_add_co_u32_e32 v6, vcc, s22, v14
	s_lshl_b32 s12, s8, 7
	s_nop 0
	v_addc_co_u32_e32 v7, vcc, 0, v15, vcc
	v_add_co_u32_e32 v10, vcc, s23, v14
	s_ashr_i32 s13, s12, 31
	s_nop 0
	v_addc_co_u32_e32 v11, vcc, 0, v15, vcc
	v_add_co_u32_e32 v48, vcc, s43, v14
	s_lshl_b64 s[12:13], s[12:13], 15
	s_nop 0
	v_addc_co_u32_e32 v49, vcc, 0, v15, vcc
	v_add_co_u32_e32 v52, vcc, s44, v14
	s_add_u32 s8, s25, s12
	s_nop 0
	v_addc_co_u32_e32 v53, vcc, 0, v15, vcc
	v_add_co_u32_e32 v56, vcc, s45, v14
	s_addc_u32 s13, s26, s13
	s_nop 0
	v_addc_co_u32_e32 v57, vcc, 0, v15, vcc
	v_add_co_u32_e32 v60, vcc, s46, v14
	s_lshl_b32 s12, s61, 1
	s_nop 0
	v_addc_co_u32_e32 v61, vcc, 0, v15, vcc
	s_add_u32 s12, s8, s12
	global_load_dwordx4 v[2:5], v[14:15], off
	s_nop 0
	global_load_dwordx4 v[6:9], v[6:7], off
	v_add_co_u32_e32 v14, vcc, s47, v14
	s_addc_u32 s13, s13, 0
	s_nop 0
	v_addc_co_u32_e32 v15, vcc, 0, v15, vcc
	global_load_dwordx4 v[10:13], v[10:11], off
	s_nop 0
	global_load_dwordx4 v[48:51], v[48:49], off
	s_nop 0
	global_load_dwordx4 v[52:55], v[52:53], off
	s_nop 0
	global_load_dwordx4 v[56:59], v[56:57], off
	s_nop 0
	global_load_dwordx4 v[60:63], v[60:61], off
	s_nop 0
	global_load_dwordx4 v[64:67], v[14:15], off
	v_lshl_add_u64 v[14:15], s[12:13], 0, v[178:179]
	v_add_co_u32_e32 v72, vcc, s48, v14
	s_waitcnt lgkmcnt(1)
	v_readfirstlane_b32 s63, v0
	v_addc_co_u32_e32 v73, vcc, 0, v15, vcc
	v_add_co_u32_e32 v76, vcc, s49, v14
	global_load_dwordx4 v[68:71], v[14:15], off
	s_nop 0
	global_load_dwordx4 v[72:75], v[72:73], off
	v_addc_co_u32_e32 v77, vcc, 0, v15, vcc
	v_add_co_u32_e32 v80, vcc, s50, v14
	v_add_u32_e32 v0, 0x2000, v196
	s_nop 0
	v_addc_co_u32_e32 v81, vcc, 0, v15, vcc
	v_add_co_u32_e32 v84, vcc, s51, v14
	global_load_dwordx4 v[76:79], v[76:77], off
	s_nop 0
	global_load_dwordx4 v[80:83], v[80:81], off
	v_addc_co_u32_e32 v85, vcc, 0, v15, vcc
	v_add_co_u32_e32 v88, vcc, s52, v14
	s_waitcnt lgkmcnt(0)
	v_readfirstlane_b32 s62, v100
	v_addc_co_u32_e32 v89, vcc, 0, v15, vcc
	v_add_co_u32_e32 v92, vcc, s53, v14
	global_load_dwordx4 v[84:87], v[84:85], off
	s_nop 0
	global_load_dwordx4 v[88:91], v[88:89], off
	v_addc_co_u32_e32 v93, vcc, 0, v15, vcc
	v_add_co_u32_e32 v14, vcc, s54, v14
	global_load_dwordx4 v[92:95], v[92:93], off
	s_nop 0
	v_addc_co_u32_e32 v15, vcc, 0, v15, vcc
	global_load_dwordx4 v[96:99], v[14:15], off
	s_waitcnt vmcnt(16)
	v_readfirstlane_b32 s64, v101
	s_cmp_eq_u32 s58, s5
	s_waitcnt vmcnt(15)
	ds_write_b128 v195, v[2:5]
	s_waitcnt vmcnt(14)
	ds_write_b128 v195, v[6:9] offset:8704
	s_waitcnt vmcnt(13)
	ds_write_b128 v195, v[10:13] offset:17408
	s_waitcnt vmcnt(12)
	ds_write_b128 v195, v[48:51] offset:26112
	s_waitcnt vmcnt(11)
	ds_write_b128 v195, v[52:55] offset:34816
	s_waitcnt vmcnt(10)
	ds_write_b128 v195, v[56:59] offset:43520
	s_waitcnt vmcnt(9)
	ds_write_b128 v195, v[60:63] offset:52224
	s_waitcnt vmcnt(8)
	ds_write_b128 v195, v[64:67] offset:60928
	s_waitcnt vmcnt(7)
	ds_write2_b64 v196, v[68:69], v[70:71] offset1:2
	s_waitcnt vmcnt(6)
	ds_write2_b64 v0, v[72:73], v[74:75] offset0:32 offset1:34
	v_add_u32_e32 v0, 0x4000, v196
	s_waitcnt vmcnt(5)
	ds_write2_b64 v0, v[76:77], v[78:79] offset0:64 offset1:66
	v_add_u32_e32 v0, 0x6000, v196
	s_waitcnt vmcnt(4)
	ds_write2_b64 v0, v[80:81], v[82:83] offset0:96 offset1:98
	v_add_u32_e32 v0, 0x8000, v196
	s_waitcnt vmcnt(3)
	ds_write2_b64 v0, v[84:85], v[86:87] offset0:128 offset1:130
	v_add_u32_e32 v0, 0xa000, v196
	s_waitcnt vmcnt(2)
	ds_write2_b64 v0, v[88:89], v[90:91] offset0:160 offset1:162
	v_add_u32_e32 v0, 0xc000, v196
	s_waitcnt vmcnt(1)
	ds_write2_b64 v0, v[92:93], v[94:95] offset0:192 offset1:194
	v_add_u32_e32 v0, 0xe000, v196
	s_waitcnt vmcnt(0)
	ds_write2_b64 v0, v[96:97], v[98:99] offset0:224 offset1:226
	s_cbranch_scc1 .LBB0_802
	s_lshl_b32 s8, s58, 13
	v_lshl_add_u64 v[2:3], v[184:185], 0, s[8:9]
	global_load_dwordx4 v[2:5], v[2:3], off
	s_waitcnt vmcnt(0)
	ds_write_b128 v183, v[2:5]
